# Accumulator zeroing with 64 v_mov_b64 instead of 128 v_mov_b32 per tile (all three GEMM instances)
# speedup vs baseline: 1.1000x; 1.0075x over previous
.LBB0_389:
	s_ashr_i32 s29, s28, 31
	s_lshl_b64 s[4:5], s[28:29], 19
	s_add_u32 s30, s12, s4
	s_addc_u32 s31, s13, s5
	s_and_b64 s[4:5], s[40:41], exec
	s_cselect_b32 s29, s31, s43
	s_cselect_b32 vcc_lo, s30, s42
	s_ashr_i32 s37, s36, 31
	s_lshl_b64 s[4:5], s[36:37], 19
	s_add_u32 s34, s17, s4
	s_addc_u32 s35, s70, s5
	s_and_b64 s[4:5], s[40:41], exec
	s_cselect_b32 s37, s35, s39
	s_cselect_b32 vcc_hi, s34, s38
	s_add_u32 s59, s38, 0x100
	v_mov_b32_e32 v74, 0
	s_addc_u32 s72, s39, 0
	s_mov_b32 s73, -2
	v_mov_b64_e32 v[2:3], 0
	v_mov_b64_e32 v[4:5], 0
	v_mov_b64_e32 v[6:7], 0
	v_mov_b64_e32 v[8:9], 0
	v_mov_b64_e32 v[10:11], 0
	v_mov_b64_e32 v[12:13], 0
	v_mov_b64_e32 v[14:15], 0
	v_mov_b64_e32 v[16:17], 0
	v_mov_b64_e32 v[18:19], 0
	v_mov_b64_e32 v[20:21], 0
	v_mov_b64_e32 v[22:23], 0
	v_mov_b64_e32 v[24:25], 0
	v_mov_b64_e32 v[26:27], 0
	v_mov_b64_e32 v[28:29], 0
	v_mov_b64_e32 v[30:31], 0
	v_mov_b64_e32 v[32:33], 0
	v_mov_b64_e32 v[34:35], 0
	v_mov_b64_e32 v[36:37], 0
	v_mov_b64_e32 v[38:39], 0
	v_mov_b64_e32 v[40:41], 0
	v_mov_b64_e32 v[42:43], 0
	v_mov_b64_e32 v[44:45], 0
	v_mov_b64_e32 v[46:47], 0
	v_mov_b64_e32 v[48:49], 0
	v_mov_b64_e32 v[50:51], 0
	v_mov_b64_e32 v[52:53], 0
	v_mov_b64_e32 v[54:55], 0
	v_mov_b64_e32 v[56:57], 0
	v_mov_b64_e32 v[58:59], 0
	v_mov_b64_e32 v[60:61], 0
	v_mov_b64_e32 v[62:63], 0
	v_mov_b64_e32 v[64:65], 0
	v_mov_b64_e32 v[66:67], 0
	v_mov_b64_e32 v[68:69], 0
	v_mov_b64_e32 v[70:71], 0
	v_mov_b64_e32 v[72:73], 0
	v_mov_b64_e32 v[74:75], 0
	v_mov_b64_e32 v[76:77], 0
	v_mov_b64_e32 v[78:79], 0
	v_mov_b64_e32 v[80:81], 0
	v_mov_b64_e32 v[82:83], 0
	v_mov_b64_e32 v[84:85], 0
	v_mov_b64_e32 v[86:87], 0
	v_mov_b64_e32 v[88:89], 0
	v_mov_b64_e32 v[90:91], 0
	v_mov_b64_e32 v[92:93], 0
	v_mov_b64_e32 v[94:95], 0
	v_mov_b64_e32 v[96:97], 0
	v_mov_b64_e32 v[98:99], 0
	v_mov_b64_e32 v[100:101], 0
	v_mov_b64_e32 v[102:103], 0
	v_mov_b64_e32 v[104:105], 0
	v_mov_b64_e32 v[106:107], 0
	v_mov_b64_e32 v[108:109], 0
	v_mov_b64_e32 v[110:111], 0
	v_mov_b64_e32 v[112:113], 0
	v_mov_b64_e32 v[114:115], 0
	v_mov_b64_e32 v[116:117], 0
	v_mov_b64_e32 v[118:119], 0
	v_mov_b64_e32 v[120:121], 0
	v_mov_b64_e32 v[122:123], 0
	v_mov_b64_e32 v[124:125], 0
	v_mov_b64_e32 v[126:127], 0
	v_mov_b64_e32 v[128:129], 0

.LBB0_451:
	s_add_u32 s30, s30, 0x80
	s_addc_u32 s31, s31, 0
	s_add_u32 s42, s34, 0x100
	v_mov_b32_e32 v2, 0
	s_addc_u32 s43, s35, 0
	s_mov_b32 s34, 0
	s_waitcnt lgkmcnt(0)
	v_mov_b64_e32 v[2:3], 0
	v_mov_b64_e32 v[4:5], 0
	v_mov_b64_e32 v[6:7], 0
	v_mov_b64_e32 v[8:9], 0
	v_mov_b64_e32 v[10:11], 0
	v_mov_b64_e32 v[12:13], 0
	v_mov_b64_e32 v[14:15], 0
	v_mov_b64_e32 v[16:17], 0
	v_mov_b64_e32 v[18:19], 0
	v_mov_b64_e32 v[20:21], 0
	v_mov_b64_e32 v[22:23], 0
	v_mov_b64_e32 v[24:25], 0
	v_mov_b64_e32 v[26:27], 0
	v_mov_b64_e32 v[28:29], 0
	v_mov_b64_e32 v[30:31], 0
	v_mov_b64_e32 v[32:33], 0
	v_mov_b64_e32 v[34:35], 0
	v_mov_b64_e32 v[36:37], 0
	v_mov_b64_e32 v[38:39], 0
	v_mov_b64_e32 v[40:41], 0
	v_mov_b64_e32 v[42:43], 0
	v_mov_b64_e32 v[44:45], 0
	v_mov_b64_e32 v[46:47], 0
	v_mov_b64_e32 v[48:49], 0
	v_mov_b64_e32 v[50:51], 0
	v_mov_b64_e32 v[52:53], 0
	v_mov_b64_e32 v[54:55], 0
	v_mov_b64_e32 v[56:57], 0
	v_mov_b64_e32 v[58:59], 0
	v_mov_b64_e32 v[60:61], 0
	v_mov_b64_e32 v[62:63], 0
	v_mov_b64_e32 v[64:65], 0
	v_mov_b64_e32 v[66:67], 0
	v_mov_b64_e32 v[68:69], 0
	v_mov_b64_e32 v[70:71], 0
	v_mov_b64_e32 v[72:73], 0
	v_mov_b64_e32 v[74:75], 0
	v_mov_b64_e32 v[76:77], 0
	v_mov_b64_e32 v[78:79], 0
	v_mov_b64_e32 v[80:81], 0
	v_mov_b64_e32 v[82:83], 0
	v_mov_b64_e32 v[84:85], 0
	v_mov_b64_e32 v[86:87], 0
	v_mov_b64_e32 v[88:89], 0
	v_mov_b64_e32 v[90:91], 0
	v_mov_b64_e32 v[92:93], 0
	v_mov_b64_e32 v[94:95], 0
	v_mov_b64_e32 v[96:97], 0
	v_mov_b64_e32 v[98:99], 0
	v_mov_b64_e32 v[100:101], 0
	v_mov_b64_e32 v[102:103], 0
	v_mov_b64_e32 v[104:105], 0
	v_mov_b64_e32 v[106:107], 0
	v_mov_b64_e32 v[108:109], 0
	v_mov_b64_e32 v[110:111], 0
	v_mov_b64_e32 v[112:113], 0
	v_mov_b64_e32 v[114:115], 0
	v_mov_b64_e32 v[116:117], 0
	v_mov_b64_e32 v[118:119], 0
	v_mov_b64_e32 v[120:121], 0
	v_mov_b64_e32 v[122:123], 0
	v_mov_b64_e32 v[124:125], 0
	v_mov_b64_e32 v[126:127], 0
	v_mov_b64_e32 v[128:129], 0

.LBB0_488:
	s_ashr_i32 s25, s24, 31
	s_lshl_b64 s[4:5], s[24:25], 19
	s_add_u32 s26, s12, s4
	s_addc_u32 s27, s13, s5
	s_and_b64 s[4:5], s[40:41], exec
	s_cselect_b32 s25, s27, s31
	s_cselect_b32 s66, s26, s30
	s_ashr_i32 s23, s22, 31
	s_lshl_b64 s[4:5], s[22:23], 19
	s_add_u32 s28, s39, s4
	s_addc_u32 s29, s42, s5
	s_and_b64 s[4:5], s[40:41], exec
	s_cselect_b32 s23, s29, s35
	s_cselect_b32 s67, s28, s34
	s_add_u32 s30, s30, 0x40080
	s_addc_u32 s31, s31, 0
	s_add_u32 s68, s34, 0x100
	v_mov_b32_e32 v2, 0
	s_addc_u32 s69, s35, 0
	s_mov_b32 s59, -2
	v_mov_b64_e32 v[2:3], 0
	v_mov_b64_e32 v[4:5], 0
	v_mov_b64_e32 v[6:7], 0
	v_mov_b64_e32 v[8:9], 0
	v_mov_b64_e32 v[10:11], 0
	v_mov_b64_e32 v[12:13], 0
	v_mov_b64_e32 v[14:15], 0
	v_mov_b64_e32 v[16:17], 0
	v_mov_b64_e32 v[18:19], 0
	v_mov_b64_e32 v[20:21], 0
	v_mov_b64_e32 v[22:23], 0
	v_mov_b64_e32 v[24:25], 0
	v_mov_b64_e32 v[26:27], 0
	v_mov_b64_e32 v[28:29], 0
	v_mov_b64_e32 v[30:31], 0
	v_mov_b64_e32 v[32:33], 0
	v_mov_b64_e32 v[34:35], 0
	v_mov_b64_e32 v[36:37], 0
	v_mov_b64_e32 v[38:39], 0
	v_mov_b64_e32 v[40:41], 0
	v_mov_b64_e32 v[42:43], 0
	v_mov_b64_e32 v[44:45], 0
	v_mov_b64_e32 v[46:47], 0
	v_mov_b64_e32 v[48:49], 0
	v_mov_b64_e32 v[50:51], 0
	v_mov_b64_e32 v[52:53], 0
	v_mov_b64_e32 v[54:55], 0
	v_mov_b64_e32 v[56:57], 0
	v_mov_b64_e32 v[58:59], 0
	v_mov_b64_e32 v[60:61], 0
	v_mov_b64_e32 v[62:63], 0
	v_mov_b64_e32 v[64:65], 0
	v_mov_b64_e32 v[66:67], 0
	v_mov_b64_e32 v[68:69], 0
	v_mov_b64_e32 v[70:71], 0
	v_mov_b64_e32 v[72:73], 0
	v_mov_b64_e32 v[74:75], 0
	v_mov_b64_e32 v[76:77], 0
	v_mov_b64_e32 v[78:79], 0
	v_mov_b64_e32 v[80:81], 0
	v_mov_b64_e32 v[82:83], 0
	v_mov_b64_e32 v[84:85], 0
	v_mov_b64_e32 v[86:87], 0
	v_mov_b64_e32 v[88:89], 0
	v_mov_b64_e32 v[90:91], 0
	v_mov_b64_e32 v[92:93], 0
	v_mov_b64_e32 v[94:95], 0
	v_mov_b64_e32 v[96:97], 0
	v_mov_b64_e32 v[98:99], 0
	v_mov_b64_e32 v[100:101], 0
	v_mov_b64_e32 v[102:103], 0
	v_mov_b64_e32 v[104:105], 0
	v_mov_b64_e32 v[106:107], 0
	v_mov_b64_e32 v[108:109], 0
	v_mov_b64_e32 v[110:111], 0
	v_mov_b64_e32 v[112:113], 0
	v_mov_b64_e32 v[114:115], 0
	v_mov_b64_e32 v[116:117], 0
	v_mov_b64_e32 v[118:119], 0
	v_mov_b64_e32 v[120:121], 0
	v_mov_b64_e32 v[122:123], 0
	v_mov_b64_e32 v[124:125], 0
	v_mov_b64_e32 v[126:127], 0
	v_mov_b64_e32 v[128:129], 0
